# gMLP group loop: staging no longer waits for the previous group's stores (first-entry drain before the loop, in-loop vmcnt waits removed)
# speedup vs baseline: 1.0098x; 1.0098x over previous
; #define LAS __attribute__((address_space(3)))
; DI s16x4 vtr(const LAS char* p) { return __builtin_bit_cast(s16x4, __builtin_amdgcn_ds_read_tr16_b64_v4i16((LAS v4i16_t*)p)); }
; DI void gmlp_unit(LAS char* lds, bf16_t* zU, const bf16_t* zV, const float* g_ln, const float* b_ln, const bf16_t* Wb, const float* b_sp, int R0, bool dummy = false) {
;     ...
;     const int q4 = (lane & 15) >> 2, p4 = lane & 3, blk = (lane >> 4) & 1, cb = wid & 3, tp = wid >> 2;
;     const int lt = tid >> 4, lc8 = (tid & 15) * 8;
;     u32x4 pw[4], pv[4]; f32x4 pg[2], pb[2];
;     ...
;     GM_FETCH(0);
;     ...
; #pragma unroll
;         for (int tb = 0; tb < 2; ++tb) { const int t = 32 * (2 * tp + tb) + r; bs[tb] = b_sp[g * 128 + t]; const bf16_t* up = zU + (size_t)(R0 + t) * 512 + g * 128 + 32 * cb + 4 * h;
; #pragma unroll
;             for (int k = 0; k < 4; ++k) uw[tb][k] = *(const u32x2*)(up + 8 * k); }
;         f32x16 a0, a1;
; #pragma unroll
;         for (int i = 0; i < 16; ++i) { a0[i] = 0.f; a1[i] = 0.f; }
;         const int tb0 = 2 * tp, tb1 = 2 * tp + 1;
;         const LAS char* vb_ = Vn + (8 * h + q4) * VP + cb * 64 + blk * 32 + p4 * 8;
;         bf16x8 af[8], b0f[8], b1f[8];
; #pragma unroll
;         for (int ss = 0; ss < 8; ++ss) {
;             if (16 * ss <= 32 * tb1 + 31) {
;                 const s16x4 lo = vtr(vb_ + (16 * ss) * VP), hi = vtr(vb_ + (16 * ss + 4) * VP);
;                 af[ss] = (bf16x8){lo[0], lo[1], lo[2], lo[3], hi[0], hi[1], hi[2], hi[3]};
;                 b1f[ss] = *(const LAS bf16x8*)(Wl + (32 * tb1 + r) * WP + (16 * ss + 8 * h) * 2);
;                 if (16 * ss <= 32 * tb0 + 31) b0f[ss] = *(const LAS bf16x8*)(Wl + (32 * tb0 + r) * WP + (16 * ss + 8 * h) * 2); } }
.LBB0_528:
	s_or_b64 exec, exec, s[6:7]
	v_ashrrev_i32_e32 v2, 4, v1
	v_lshlrev_b32_e32 v21, 3, v1
	v_and_b32_e32 v22, 0x78, v21
	v_add_u32_e32 v8, s9, v2
	v_lshlrev_b32_e32 v4, 1, v22
	v_mov_b32_e32 v5, v0
	v_ashrrev_i32_e32 v9, 31, v8
	v_lshl_add_u64 v[10:11], s[88:89], 0, v[4:5]
	v_lshlrev_b32_e32 v12, 7, v2
	v_lshlrev_b64 v[8:9], 10, v[8:9]
	v_add_u32_e32 v23, 32, v2
	v_ashrrev_i32_e32 v13, 31, v12
	v_lshl_add_u64 v[8:9], v[10:11], 0, v[8:9]
	v_lshlrev_b32_e32 v10, 7, v23
	v_lshl_add_u64 v[6:7], s[90:91], 0, v[4:5]
	v_lshlrev_b64 v[12:13], 1, v[12:13]
	v_ashrrev_i32_e32 v11, 31, v10
	v_lshl_add_u64 v[14:15], v[6:7], 0, v[12:13]
	v_lshlrev_b64 v[10:11], 1, v[10:11]
	s_mov_b32 s9, 0x8000
	global_load_dwordx4 v[34:37], v[14:15], off
	global_load_dwordx4 v[38:41], v[8:9], off
	v_lshl_add_u64 v[14:15], v[6:7], 0, v[10:11]
	v_add_co_u32_e32 v16, vcc, s9, v8
	v_add_u32_e32 v24, 64, v2
	s_nop 0
	v_addc_co_u32_e32 v17, vcc, 0, v9, vcc
	global_load_dwordx4 v[42:45], v[14:15], off
	global_load_dwordx4 v[46:49], v[16:17], off
	v_lshlrev_b32_e32 v14, 7, v24
	v_ashrrev_i32_e32 v15, 31, v14
	v_lshlrev_b64 v[14:15], 1, v[14:15]
	s_mov_b32 s9, 0x10000
	v_lshl_add_u64 v[16:17], v[6:7], 0, v[14:15]
	v_add_co_u32_e32 v18, vcc, s9, v8
	s_mov_b32 s9, 0x18000
	s_nop 0
	v_addc_co_u32_e32 v19, vcc, 0, v9, vcc
	global_load_dwordx4 v[50:53], v[16:17], off
	global_load_dwordx4 v[54:57], v[18:19], off
	v_add_u32_e32 v18, 0x60, v2
	v_lshlrev_b32_e32 v16, 7, v18
	v_ashrrev_i32_e32 v17, 31, v16
	v_lshlrev_b64 v[16:17], 1, v[16:17]
	v_lshl_add_u64 v[6:7], v[6:7], 0, v[16:17]
	v_add_co_u32_e32 v8, vcc, s9, v8
	v_lshrrev_b32_e32 v5, 5, v66
	s_nop 0
	v_addc_co_u32_e32 v9, vcc, 0, v9, vcc
	global_load_dwordx4 v[58:61], v[6:7], off
	global_load_dwordx4 v[62:65], v[8:9], off
	v_lshlrev_b32_e32 v6, 2, v22
	global_load_dwordx4 v[66:69], v6, s[36:37] offset:16
	global_load_dwordx4 v[74:77], v6, s[38:39] offset:16
	global_load_dwordx4 v[70:73], v6, s[36:37]
	global_load_dwordx4 v[78:81], v6, s[38:39]
	s_ashr_i32 s9, s8, 8
	s_and_b32 s8, s8, 0xc0
	s_bfe_u32 s7, s85, 0x90007
	v_mov_b32_e32 v7, v0
	s_lshl_b32 s10, s9, 6
	s_add_i32 s11, s8, 0
	s_lshl_b32 s6, s7, 7
	s_lshl_b32 s7, s7, 17
	v_lshl_add_u64 v[180:181], s[36:37], 0, v[6:7]
	v_lshl_add_u64 v[182:183], s[38:39], 0, v[6:7]
	v_mov_b32_e32 v7, s11
	s_or_b32 s11, s10, 63
	s_or_b32 s12, s10, 31
	s_cmp_gt_i32 s9, -1
	s_cselect_b64 s[94:95], -1, 0
	s_cmp_gt_i32 s12, 31
	s_cselect_b64 s[96:97], -1, 0
	s_cmp_gt_i32 s12, 47
	s_cselect_b64 s[42:43], -1, 0
	s_cmp_gt_i32 s11, 63
	s_cselect_b64 s[28:29], -1, 0
	s_cmp_gt_i32 s12, 63
	s_cselect_b64 s[40:41], -1, 0
	s_cmpk_gt_i32 s11, 0x4f
	s_cselect_b64 s[46:47], -1, 0
	s_cmpk_gt_i32 s12, 0x4f
	v_bfe_u32 v8, v1, 2, 2
	s_cselect_b64 s[44:45], -1, 0
	s_cmpk_gt_i32 s11, 0x5f
	v_lshl_or_b32 v6, v5, 3, v8
	s_cselect_b64 s[56:57], -1, 0
	s_cmpk_gt_i32 s12, 0x5f
	v_and_b32_e32 v3, 31, v1
	v_mad_u32_u24 v6, v6, s5, v7
	v_lshlrev_b32_e32 v7, 1, v1
	s_cselect_b64 s[58:59], -1, 0
	s_cmpk_gt_i32 s11, 0x6f
	v_lshrrev_b32_e32 v20, 2, v1
	v_add_u32_e32 v230, 0, v4
	v_or_b32_e32 v4, s10, v3
	v_and_b32_e32 v7, 32, v7
	v_and_b32_e32 v8, 24, v21
	s_cselect_b64 s[34:35], -1, 0
	s_cmpk_gt_i32 s12, 0x6f
	v_lshlrev_b32_e32 v1, 4, v1
	v_add3_u32 v231, v6, v7, v8
	v_mul_lo_u32 v6, v4, s68
	v_lshlrev_b32_e32 v25, 4, v5
	s_cselect_b64 s[52:53], -1, 0
	v_ashrrev_i32_e32 v5, 31, v4
	v_and_b32_e32 v1, 0xf0, v1
	s_add_i32 s9, s6, s10
	v_add_u32_e32 v19, 0, v6
	v_lshl_add_u64 v[184:185], v[4:5], 2, s[92:93]
	v_or_b32_e32 v4, 0x2788000, v1
	v_mov_b32_e32 v5, v0
	v_or_b32_e32 v6, s9, v3
	v_lshl_add_u64 v[186:187], v[4:5], 0, v[16:17]
	v_lshl_add_u64 v[188:189], v[4:5], 0, v[14:15]
	v_lshl_add_u64 v[190:191], v[4:5], 0, v[10:11]
	v_lshl_add_u64 v[194:195], v[4:5], 0, v[12:13]
	v_or_b32_e32 v4, 32, v6
	v_ashrrev_i32_e32 v7, 31, v6
	v_ashrrev_i32_e32 v5, 31, v4
	v_lshlrev_b64 v[8:9], 10, v[6:7]
	v_and_b32_e32 v3, 8, v20
	v_lshlrev_b64 v[4:5], 10, v[4:5]
	v_or3_b32 v8, v8, s8, v3
	v_or3_b32 v4, v4, s8, v3
	s_add_u32 s8, s7, 0x8800100
	v_ashrrev_i32_e32 v3, 31, v2
	v_mul_lo_u32 v21, v2, s68
	v_lshlrev_b32_e32 v234, 3, v2
	v_mul_lo_u32 v235, v2, s5
	s_addc_u32 s9, 0, 0
	v_lshlrev_b64 v[2:3], 10, v[2:3]
	v_lshl_add_u64 v[198:199], s[8:9], 0, v[2:3]
	v_add_u32_e32 v2, s6, v23
	v_ashrrev_i32_e32 v3, 31, v2
	v_lshlrev_b64 v[2:3], 10, v[2:3]
	v_or_b32_e32 v2, v2, v1
	v_lshl_add_u64 v[200:201], v[2:3], 0, s[72:73]
	v_add_u32_e32 v2, s6, v24
	v_ashrrev_i32_e32 v3, 31, v2
	v_lshlrev_b64 v[2:3], 10, v[2:3]
	v_or_b32_e32 v2, v2, v1
	v_lshl_add_u64 v[202:203], v[2:3], 0, s[72:73]
	v_add_u32_e32 v2, s6, v18
	v_ashrrev_i32_e32 v3, 31, v2
	v_lshlrev_b64 v[2:3], 10, v[2:3]
	v_add_u32_e32 v22, 0x2800, v235
	v_or_b32_e32 v2, v2, v1
	v_add_u32_e32 v233, 0x8800, v231
	v_lshlrev_b32_e32 v236, 3, v23
	v_lshlrev_b32_e32 v237, 3, v24
	v_lshlrev_b32_e32 v238, 3, v18
	v_lshl_add_u64 v[192:193], v[8:9], 0, s[70:71]
	v_lshl_add_u64 v[196:197], v[4:5], 0, s[70:71]
	v_or_b32_e32 v198, v198, v1
	v_lshl_add_u64 v[204:205], v[2:3], 0, s[72:73]
	s_mov_b64 s[54:55], 0
	v_add_u32_e32 v239, v230, v21
	v_add_u32_e32 v240, v230, v22
	v_add_u32_e32 v241, v19, v25
	s_waitcnt vmcnt(0)
	s_branch .LBB0_530

; #define LAS __attribute__((address_space(3)))
; DI unsigned cvtpk(float lo, float hi) { f32x2_t v = {lo, hi}; bf16x2_t b = __builtin_convertvector(v, bf16x2_t); return __builtin_bit_cast(unsigned, b); }
; DI float bflo(unsigned w) { return __uint_as_float(w << 16); }
; DI float bfhi(unsigned w) { return __uint_as_float(w & 0xffff0000u); }
; DI void gmlp_unit(LAS char* lds, bf16_t* zU, const bf16_t* zV, const float* g_ln, const float* b_ln, const bf16_t* Wb, const float* b_sp, int R0, bool dummy = false) {
;     ...
;     GM_FETCH(0);
; #pragma unroll 1
;     for (int g = 0; g < 4; ++g) {
;         __syncthreads();
; #pragma unroll
;         for (int i = 0; i < 4; ++i) { const int s = lt + 32 * i;
;             *(LAS u32x4*)(Wl + s * WP + lc8 * 2) = pw[i];
;             const u32x4 w = pv[i]; float v[8] = {bflo(w.x), bfhi(w.x), bflo(w.y), bfhi(w.y), bflo(w.z), bfhi(w.z), bflo(w.w), bfhi(w.w)};
;             const float mu = St[2 * s], rsd = St[2 * s + 1];
; #pragma unroll
;             for (int e = 0; e < 8; ++e) v[e] = (v[e] - mu) * rsd * pg[e >> 2][e & 3] + pb[e >> 2][e & 3];
;             u32x4 o; o.x = cvtpk(v[0], v[1]); o.y = cvtpk(v[2], v[3]); o.z = cvtpk(v[4], v[5]); o.w = cvtpk(v[6], v[7]); *(LAS u32x4*)(Vn + s * VP + lc8 * 2) = o; }
;         __syncthreads();
;         if (g + 1 < 4) GM_FETCH(g + 1);
.LBB0_530:
	s_add_i32 s6, 0, 0x12800
	s_waitcnt lgkmcnt(0)
	s_barrier
	ds_write_b128 v239, v[34:37]
	v_add_u32_e32 v1, s6, v234
	ds_read_b64 v[2:3], v1
	v_lshlrev_b32_e32 v4, 16, v38
	v_and_b32_e32 v5, 0xffff0000, v38
	v_lshlrev_b32_e32 v6, 16, v39
	v_and_b32_e32 v7, 0xffff0000, v39
	v_lshlrev_b32_e32 v8, 16, v40
	v_and_b32_e32 v9, 0xffff0000, v40
	v_lshlrev_b32_e32 v10, 16, v41
	v_and_b32_e32 v11, 0xffff0000, v41
	s_waitcnt lgkmcnt(0)
	v_pk_add_f32 v[4:5], v[4:5], v[2:3] op_sel_hi:[1,0] neg_lo:[0,1] neg_hi:[0,1]
	v_pk_add_f32 v[6:7], v[6:7], v[2:3] op_sel_hi:[1,0] neg_lo:[0,1] neg_hi:[0,1]
	v_pk_add_f32 v[8:9], v[8:9], v[2:3] op_sel_hi:[1,0] neg_lo:[0,1] neg_hi:[0,1]
	v_pk_add_f32 v[10:11], v[10:11], v[2:3] op_sel_hi:[1,0] neg_lo:[0,1] neg_hi:[0,1]
	v_pk_mul_f32 v[4:5], v[2:3], v[4:5] op_sel:[1,0]
	v_pk_mul_f32 v[6:7], v[2:3], v[6:7] op_sel:[1,0]
	v_pk_mul_f32 v[8:9], v[2:3], v[8:9] op_sel:[1,0]
	v_pk_mul_f32 v[2:3], v[2:3], v[10:11] op_sel:[1,0]
	v_pk_fma_f32 v[4:5], v[70:71], v[4:5], v[78:79]
	v_pk_fma_f32 v[6:7], v[72:73], v[6:7], v[80:81]
	v_pk_fma_f32 v[8:9], v[66:67], v[8:9], v[74:75]
	v_pk_fma_f32 v[10:11], v[68:69], v[2:3], v[76:77]
	v_cvt_pk_bf16_f32 v2, v4, v5
	v_cvt_pk_bf16_f32 v3, v6, v7
	v_cvt_pk_bf16_f32 v4, v8, v9
	v_cvt_pk_bf16_f32 v5, v10, v11
	v_add_u32_e32 v1, v230, v235
	ds_write_b128 v1, v[2:5] offset:34816
	ds_write_b128 v239, v[42:45] offset:8704
	v_add_u32_e32 v2, s6, v236
	ds_read_b64 v[2:3], v2
	v_lshlrev_b32_e32 v4, 16, v46
	v_and_b32_e32 v5, 0xffff0000, v46
	v_lshlrev_b32_e32 v6, 16, v47
	v_and_b32_e32 v7, 0xffff0000, v47
	v_lshlrev_b32_e32 v8, 16, v48
	v_and_b32_e32 v9, 0xffff0000, v48
	v_lshlrev_b32_e32 v10, 16, v49
	v_and_b32_e32 v11, 0xffff0000, v49
	s_waitcnt lgkmcnt(0)
	v_pk_add_f32 v[4:5], v[4:5], v[2:3] op_sel_hi:[1,0] neg_lo:[0,1] neg_hi:[0,1]
	v_pk_add_f32 v[6:7], v[6:7], v[2:3] op_sel_hi:[1,0] neg_lo:[0,1] neg_hi:[0,1]
	v_pk_add_f32 v[8:9], v[8:9], v[2:3] op_sel_hi:[1,0] neg_lo:[0,1] neg_hi:[0,1]
	v_pk_add_f32 v[10:11], v[10:11], v[2:3] op_sel_hi:[1,0] neg_lo:[0,1] neg_hi:[0,1]
	v_pk_mul_f32 v[4:5], v[2:3], v[4:5] op_sel:[1,0]
	v_pk_mul_f32 v[6:7], v[2:3], v[6:7] op_sel:[1,0]
	v_pk_mul_f32 v[8:9], v[2:3], v[8:9] op_sel:[1,0]
	v_pk_mul_f32 v[2:3], v[2:3], v[10:11] op_sel:[1,0]
	v_pk_fma_f32 v[4:5], v[70:71], v[4:5], v[78:79]
	v_pk_fma_f32 v[6:7], v[72:73], v[6:7], v[80:81]
	v_pk_fma_f32 v[8:9], v[66:67], v[8:9], v[74:75]
	v_pk_fma_f32 v[10:11], v[68:69], v[2:3], v[76:77]
	v_cvt_pk_bf16_f32 v2, v4, v5
	v_cvt_pk_bf16_f32 v3, v6, v7
	v_cvt_pk_bf16_f32 v4, v8, v9
	v_cvt_pk_bf16_f32 v5, v10, v11
	ds_write_b128 v1, v[2:5] offset:45056
	ds_write_b128 v239, v[50:53] offset:17408
	v_add_u32_e32 v2, s6, v237
	ds_read_b64 v[2:3], v2
	v_lshlrev_b32_e32 v4, 16, v54
	v_and_b32_e32 v5, 0xffff0000, v54
	v_lshlrev_b32_e32 v6, 16, v55
	v_and_b32_e32 v7, 0xffff0000, v55
	v_lshlrev_b32_e32 v8, 16, v56
	v_and_b32_e32 v9, 0xffff0000, v56
	v_lshlrev_b32_e32 v10, 16, v57
	v_and_b32_e32 v11, 0xffff0000, v57
	s_waitcnt lgkmcnt(0)
	v_pk_add_f32 v[4:5], v[4:5], v[2:3] op_sel_hi:[1,0] neg_lo:[0,1] neg_hi:[0,1]
	v_pk_add_f32 v[6:7], v[6:7], v[2:3] op_sel_hi:[1,0] neg_lo:[0,1] neg_hi:[0,1]
	v_pk_add_f32 v[8:9], v[8:9], v[2:3] op_sel_hi:[1,0] neg_lo:[0,1] neg_hi:[0,1]
	v_pk_add_f32 v[10:11], v[10:11], v[2:3] op_sel_hi:[1,0] neg_lo:[0,1] neg_hi:[0,1]
	v_pk_mul_f32 v[4:5], v[2:3], v[4:5] op_sel:[1,0]
	v_pk_mul_f32 v[6:7], v[2:3], v[6:7] op_sel:[1,0]
	v_pk_mul_f32 v[8:9], v[2:3], v[8:9] op_sel:[1,0]
	v_pk_mul_f32 v[2:3], v[2:3], v[10:11] op_sel:[1,0]
	v_pk_fma_f32 v[4:5], v[70:71], v[4:5], v[78:79]
	v_pk_fma_f32 v[6:7], v[72:73], v[6:7], v[80:81]
	v_pk_fma_f32 v[8:9], v[66:67], v[8:9], v[74:75]
	v_pk_fma_f32 v[10:11], v[68:69], v[2:3], v[76:77]
	v_cvt_pk_bf16_f32 v2, v4, v5
	v_cvt_pk_bf16_f32 v3, v6, v7
	v_cvt_pk_bf16_f32 v4, v8, v9
	v_cvt_pk_bf16_f32 v5, v10, v11
	ds_write_b128 v1, v[2:5] offset:55296
	ds_write_b128 v239, v[58:61] offset:26112
	v_add_u32_e32 v1, s6, v238
	ds_read_b64 v[2:3], v1
	v_lshlrev_b32_e32 v4, 16, v62
	v_and_b32_e32 v5, 0xffff0000, v62
	v_lshlrev_b32_e32 v6, 16, v63
	v_and_b32_e32 v7, 0xffff0000, v63
	v_lshlrev_b32_e32 v8, 16, v64
	v_and_b32_e32 v9, 0xffff0000, v64
	v_lshlrev_b32_e32 v10, 16, v65
	v_and_b32_e32 v11, 0xffff0000, v65
	s_waitcnt lgkmcnt(0)
	v_pk_add_f32 v[4:5], v[4:5], v[2:3] op_sel_hi:[1,0] neg_lo:[0,1] neg_hi:[0,1]
	v_pk_add_f32 v[6:7], v[6:7], v[2:3] op_sel_hi:[1,0] neg_lo:[0,1] neg_hi:[0,1]
	v_pk_add_f32 v[8:9], v[8:9], v[2:3] op_sel_hi:[1,0] neg_lo:[0,1] neg_hi:[0,1]
	v_pk_add_f32 v[10:11], v[10:11], v[2:3] op_sel_hi:[1,0] neg_lo:[0,1] neg_hi:[0,1]
	v_pk_mul_f32 v[4:5], v[2:3], v[4:5] op_sel:[1,0]
	v_pk_mul_f32 v[6:7], v[2:3], v[6:7] op_sel:[1,0]
	v_pk_mul_f32 v[8:9], v[2:3], v[8:9] op_sel:[1,0]
	v_pk_mul_f32 v[2:3], v[2:3], v[10:11] op_sel:[1,0]
	v_pk_fma_f32 v[4:5], v[70:71], v[4:5], v[78:79]
	v_pk_fma_f32 v[6:7], v[72:73], v[6:7], v[80:81]
	v_pk_fma_f32 v[8:9], v[66:67], v[8:9], v[74:75]
	v_pk_fma_f32 v[10:11], v[68:69], v[2:3], v[76:77]
	v_cvt_pk_bf16_f32 v2, v4, v5
	v_cvt_pk_bf16_f32 v3, v6, v7
	v_cvt_pk_bf16_f32 v4, v8, v9
	v_cvt_pk_bf16_f32 v5, v10, v11
	s_cmpk_eq_i32 s54, 0x600
	ds_write_b128 v240, v[2:5] offset:55296
	s_waitcnt lgkmcnt(0)
	s_barrier
	s_cbranch_scc1 .LBB0_532
	v_lshl_add_u64 v[2:3], s[86:87], 0, v[194:195]
	v_lshl_add_u64 v[4:5], s[86:87], 0, v[198:199]
	global_load_dwordx4 v[34:37], v[2:3], off
	global_load_dwordx4 v[38:41], v[4:5], off
	v_lshl_add_u64 v[2:3], s[86:87], 0, v[190:191]
	v_lshl_add_u64 v[4:5], s[86:87], 0, v[200:201]
	global_load_dwordx4 v[42:45], v[2:3], off
	global_load_dwordx4 v[46:49], v[4:5], off
	v_lshl_add_u64 v[2:3], s[86:87], 0, v[188:189]
	v_lshl_add_u64 v[4:5], s[86:87], 0, v[202:203]
	global_load_dwordx4 v[50:53], v[2:3], off
	global_load_dwordx4 v[54:57], v[4:5], off
	v_lshl_add_u64 v[2:3], s[86:87], 0, v[186:187]
	v_lshl_add_u64 v[4:5], s[86:87], 0, v[204:205]
	global_load_dwordx4 v[58:61], v[2:3], off
	global_load_dwordx4 v[62:65], v[4:5], off
	v_lshl_add_u64 v[2:3], v[180:181], 0, s[54:55]
	global_load_dwordx4 v[66:69], v[2:3], off offset:528
	global_load_dwordx4 v[70:73], v[2:3], off offset:512
	v_lshl_add_u64 v[2:3], v[182:183], 0, s[54:55]
	global_load_dwordx4 v[74:77], v[2:3], off offset:528
	global_load_dwordx4 v[78:81], v[2:3], off offset:512
